# diff-attention MFMA phase: P.V MFMAs of the previous tile hoisted to the phase head, K-fragment reads and bias-state scalar work moved into their shadow, LDS waits re-derived
# speedup vs baseline: 1.0386x; 1.0171x over previous
; #define LAS3 __attribute__((address_space(3)))
; #define ATT_BAR_V(full) do { if (full) { if (MODE) ATT_WAIT_BAR(4); else ATT_WAIT_BAR(2); } else ATT_WAIT_BAR(0); } while (0)
; #define ATT_BAR_L() asm volatile("s_waitcnt lgkmcnt(0)\n\ts_barrier" ::: "memory")
; #define ATT_SB() __builtin_amdgcn_sched_barrier(0)
; template <int MODE>
; __device__ __forceinline__ void attn_unit(const Tensors& T0, int ureq, int b, int hh, int qblk, LAS3 char* shm, const bool dummy = false) {
;     ...
;     float cb = 0.f; bool near = true;
;     if (MODE) { if (k0 + 63 - Q0 <= -91) { cb = cbL; near = false; } else if (k0 - (Q0 + 127) >= 91) { cb = cbR; near = false; } }
;     if (cb != curcb) { curcb = cb;
; #pragma unroll
;       for (int r = 0; r < 16; ++r) negm[r] = cb - mhat; }
;     f32x16 C0 = negm, C1 = negm;
;     if (!(ATT_ABL == 4 && dummy)) { const int kso = (i & 3) * SLOTB; const int vp = ((i - 1) & 3) * SLOTB;
;       bf16x8 kf[8];
; #pragma unroll
;       for (int d0 = 0; d0 < 2; ++d0) { kf[2 * d0] = *(const LAS3 bf16x8*)(kp[d0] + kso); kf[2 * d0 + 1] = *(const LAS3 bf16x8*)(kp[d0] + kso + 4096); }
;       if (i > 0) { ATT_VREAD(vB, 1, vp); }
;       ATT_SB();
;       if (i > 0) { ATT_PVK_RD(vA, 0, vp); }
;       C0 = __builtin_amdgcn_mfma_f32_32x32x16_bf16(kf[0], qr[0], negm, 0, 0, 0); C1 = __builtin_amdgcn_mfma_f32_32x32x16_bf16(kf[1], qr[0], negm, 0, 0, 0);
;       C0 = __builtin_amdgcn_mfma_f32_32x32x16_bf16(kf[2], qr[1], C0, 0, 0, 0); C1 = __builtin_amdgcn_mfma_f32_32x32x16_bf16(kf[3], qr[1], C1, 0, 0, 0);
;       ATT_SB();
; #pragma unroll
;       for (int d0 = 2; d0 < 4; ++d0) { kf[2 * d0] = *(const LAS3 bf16x8*)(kp[d0] + kso); kf[2 * d0 + 1] = *(const LAS3 bf16x8*)(kp[d0] + kso + 4096); }
;       ATT_SB();
;       if (i > 0) { ATT_PVK_RD(vB, 1, vp); }
; #pragma unroll
;       for (int d0 = 2; d0 < 4; ++d0) { C0 = __builtin_amdgcn_mfma_f32_32x32x16_bf16(kf[2 * d0], qr[d0], C0, 0, 0, 0); C1 = __builtin_amdgcn_mfma_f32_32x32x16_bf16(kf[2 * d0 + 1], qr[d0], C1, 0, 0, 0); }
;       ATT_SB();
;       if (i > 0) { ATT_PVK(vA, 2); ATT_PVK(vB, 3); } }
;     asm volatile("" : "+v"(C0), "+v"(C1));
; #pragma unroll
;     for (int d = 0; d < ND; ++d) asm volatile("" : "+v"(o[d]));
;     if (grp == 0) ATT_BAR_L(); else ATT_BAR_V(i + 2 < NT);
.LBB0_105:
	s_setprio 1
	s_add_i32 s18, s98, 0xffff0000
	s_and_b32 s18, s18, 0x18000
	v_add_u32_e32 v104, s18, v194
	s_add_i32 s97, s98, 0x8000
	s_and_b32 s99, s97, 0x18000
	ds_read_b128 v[100:103], v104
	ds_read_b128 v[206:209], v104 offset:4096
	v_mfma_f32_32x32x16_bf16 v[48:63], v[96:99], v[156:159], v[48:63]
	v_add_u32_e32 v205, s99, v193
	v_add_u32_e32 v242, s99, v190
	v_add_u32_e32 v104, s18, v195
	ds_read_b64_tr_b16 v[156:157], v205 offset:20480
	ds_read_b64_tr_b16 v[158:159], v205 offset:21504
	ds_read_b128 v[210:213], v104
	ds_read_b128 v[214:217], v104 offset:4096
	v_mfma_f32_32x32x16_bf16 v[64:79], v[96:99], v[152:155], v[64:79]
	ds_read_b64_tr_b16 v[152:153], v242 offset:20480
	ds_read_b64_tr_b16 v[154:155], v242 offset:21504
	ds_read_b64_tr_b16 v[218:219], v205 offset:18432
	ds_read_b64_tr_b16 v[220:221], v205 offset:19456
	s_add_i32 s96, s93, -2
	s_add_i32 s8, s95, 0xffffff67
	v_mfma_f32_32x32x16_bf16 v[32:47], v[96:99], v[148:151], v[32:47]
	ds_read_b64_tr_b16 v[148:149], v205 offset:28672
	ds_read_b64_tr_b16 v[150:151], v205 offset:29696
	ds_read_b64_tr_b16 v[222:223], v242 offset:18432
	ds_read_b64_tr_b16 v[224:225], v242 offset:19456
	s_cmpk_gt_i32 s8, 0xff66
	s_cselect_b64 vcc, -1, 0
	s_cmpk_gt_i32 s8, 0xd9
	s_cselect_b64 s[8:9], -1, 0
	v_mfma_f32_32x32x16_bf16 v[16:31], v[96:99], v[144:147], v[16:31]
	ds_read_b64_tr_b16 v[144:145], v242 offset:28672
	ds_read_b64_tr_b16 v[146:147], v242 offset:29696
	ds_read_b64_tr_b16 v[226:227], v205 offset:26624
	ds_read_b64_tr_b16 v[228:229], v205 offset:27648
	ds_read_b64_tr_b16 v[230:231], v242 offset:26624
	ds_read_b64_tr_b16 v[232:233], v242 offset:27648
	v_cndmask_b32_e64 v250, 0, v192, s[8:9]
	v_cndmask_b32_e32 v204, v191, v250, vcc
	v_add_u32_e32 v248, s18, v193
	v_add_u32_e32 v249, s18, v190
	v_cmp_neq_f32_e64 s[8:9], v204, v201
	v_add_u32_e32 v238, s18, v197
	s_and_b64 vcc, exec, s[8:9]
	s_cbranch_vccz .Lm1_negm_keep
	v_sub_f32_e32 v80, v204, v202
	v_mov_b32_e32 v201, v204
	v_mov_b32_e32 v81, v80
	v_mov_b32_e32 v82, v80
	v_mov_b32_e32 v83, v80
	v_mov_b32_e32 v84, v80
	v_mov_b32_e32 v85, v80
	v_mov_b32_e32 v86, v80
	v_mov_b32_e32 v87, v80
	v_mov_b32_e32 v88, v80
	v_mov_b32_e32 v89, v80
	v_mov_b32_e32 v90, v80
	v_mov_b32_e32 v91, v80
	v_mov_b32_e32 v92, v80
	v_mov_b32_e32 v93, v80
	v_mov_b32_e32 v94, v80
	v_mov_b32_e32 v95, v80
	s_nop 0
.Lm1_negm_keep:
	s_waitcnt lgkmcnt(15)
	v_mfma_f32_32x32x16_bf16 v[112:127], v[100:103], v[128:131], v[80:95]
	v_mfma_f32_32x32x16_bf16 v[96:111], v[206:209], v[128:131], v[80:95]
	s_waitcnt lgkmcnt(14)
	v_mfma_f32_32x32x16_bf16 v[112:127], v[210:213], v[132:135], v[112:127]
	v_add_u32_e32 v210, s18, v196
	ds_read_b128 v[206:209], v210
	ds_read_b128 v[210:213], v210 offset:4096
	ds_read_b128 v[234:237], v238
	ds_read_b128 v[238:241], v238 offset:4096
	v_mfma_f32_32x32x16_bf16 v[96:111], v[214:217], v[132:135], v[96:111]
	s_waitcnt lgkmcnt(14)
	v_mfma_f32_32x32x16_bf16 v[48:63], v[168:171], v[218:221], v[48:63]
	ds_read_b64_tr_b16 v[214:215], v205 offset:22528
	ds_read_b64_tr_b16 v[216:217], v205 offset:23552
	s_waitcnt lgkmcnt(12)
	v_mfma_f32_32x32x16_bf16 v[64:79], v[168:171], v[222:225], v[64:79]
	ds_read_b64_tr_b16 v[218:219], v242 offset:22528
	ds_read_b64_tr_b16 v[220:221], v242 offset:23552
	s_waitcnt lgkmcnt(10)
	v_mfma_f32_32x32x16_bf16 v[32:47], v[168:171], v[226:229], v[32:47]
	ds_read_b64_tr_b16 v[222:223], v205 offset:30720
	ds_read_b64_tr_b16 v[224:225], v205 offset:31744
	s_waitcnt lgkmcnt(10)
	v_mfma_f32_32x32x16_bf16 v[16:31], v[168:171], v[230:233], v[16:31]
	ds_read_b64_tr_b16 v[168:169], v242 offset:30720
	ds_read_b64_tr_b16 v[170:171], v242 offset:31744
	s_waitcnt lgkmcnt(11)
	v_mfma_f32_32x32x16_bf16 v[112:127], v[206:209], v[136:139], v[112:127]
	s_waitcnt lgkmcnt(10)
	v_mfma_f32_32x32x16_bf16 v[96:111], v[210:213], v[136:139], v[96:111]
	s_waitcnt lgkmcnt(9)
	v_mfma_f32_32x32x16_bf16 v[112:127], v[234:237], v[140:143], v[112:127]
	s_waitcnt lgkmcnt(8)
	v_mfma_f32_32x32x16_bf16 v[96:111], v[238:241], v[140:143], v[96:111]
	v_mfma_f32_32x32x16_bf16 v[48:63], v[164:167], v[156:159], v[48:63]
	ds_read_b64_tr_b16 v[156:157], v248 offset:16384
	ds_read_b64_tr_b16 v[158:159], v248 offset:17408
	v_mfma_f32_32x32x16_bf16 v[64:79], v[164:167], v[152:155], v[64:79]
	ds_read_b64_tr_b16 v[152:153], v249 offset:16384
	ds_read_b64_tr_b16 v[154:155], v249 offset:17408
	v_mfma_f32_32x32x16_bf16 v[32:47], v[164:167], v[148:151], v[32:47]
	ds_read_b64_tr_b16 v[148:149], v248 offset:24576
	ds_read_b64_tr_b16 v[150:151], v248 offset:25600
	v_mfma_f32_32x32x16_bf16 v[16:31], v[164:167], v[144:147], v[16:31]
	ds_read_b64_tr_b16 v[144:145], v249 offset:24576
	ds_read_b64_tr_b16 v[146:147], v249 offset:25600
	s_waitcnt lgkmcnt(14)
	v_mfma_f32_32x32x16_bf16 v[48:63], v[160:163], v[214:217], v[48:63]
	s_waitcnt lgkmcnt(12)
	v_mfma_f32_32x32x16_bf16 v[64:79], v[160:163], v[218:221], v[64:79]
	s_waitcnt lgkmcnt(10)
	v_mfma_f32_32x32x16_bf16 v[32:47], v[160:163], v[222:225], v[32:47]
	s_waitcnt lgkmcnt(8)
	v_mfma_f32_32x32x16_bf16 v[16:31], v[160:163], v[168:171], v[16:31]
	s_waitcnt lgkmcnt(0)
	s_barrier

; #define LAS3 __attribute__((address_space(3)))
; #define ATT_BAR_V(full) do { if (full) { if (MODE) ATT_WAIT_BAR(4); else ATT_WAIT_BAR(2); } else ATT_WAIT_BAR(0); } while (0)
; #define ATT_BAR_L() asm volatile("s_waitcnt lgkmcnt(0)\n\ts_barrier" ::: "memory")
; #define ATT_SB() __builtin_amdgcn_sched_barrier(0)
; #define ATT_VREAD(buf, ks, vso) do { _Pragma("unroll") for (int d0 = 0; d0 < ND; ++d0) { const lds_cptr vq_ = ((d0 & 1) ? vpo : vpe) + (vso) + (d0 >> 1) * 8192 + (ks) * 2048; \
;       const s16x4 lo = vtr(vq_), hi4 = vtr(vq_ + 1024); \
;       buf[d0] = (bf16x8){lo[0], lo[1], lo[2], lo[3], hi4[0], hi4[1], hi4[2], hi4[3]}; } } while (0)
; template <int MODE>
; __device__ __forceinline__ void attn_unit(const Tensors& T0, int ureq, int b, int hh, int qblk, LAS3 char* shm, const bool dummy = false) {
;     ...
;     if (!(ATT_ABL == 4 && dummy)) { const int kso = (i & 3) * SLOTB; const int vp = ((i - 1) & 3) * SLOTB;
;       bf16x8 kf[8];
; #pragma unroll
;       for (int d0 = 0; d0 < 2; ++d0) { kf[2 * d0] = *(const LAS3 bf16x8*)(kp[d0] + kso); kf[2 * d0 + 1] = *(const LAS3 bf16x8*)(kp[d0] + kso + 4096); }
;       if (i > 0) { ATT_VREAD(vB, 1, vp); }
;       ATT_SB();
;       if (i > 0) { ATT_PVK_RD(vA, 0, vp); }
;       C0 = __builtin_amdgcn_mfma_f32_32x32x16_bf16(kf[0], qr[0], negm, 0, 0, 0); C1 = __builtin_amdgcn_mfma_f32_32x32x16_bf16(kf[1], qr[0], negm, 0, 0, 0);
;       C0 = __builtin_amdgcn_mfma_f32_32x32x16_bf16(kf[2], qr[1], C0, 0, 0, 0); C1 = __builtin_amdgcn_mfma_f32_32x32x16_bf16(kf[3], qr[1], C1, 0, 0, 0);
;       ATT_SB();
; #pragma unroll
;       for (int d0 = 2; d0 < 4; ++d0) { kf[2 * d0] = *(const LAS3 bf16x8*)(kp[d0] + kso); kf[2 * d0 + 1] = *(const LAS3 bf16x8*)(kp[d0] + kso + 4096); }
;       ATT_SB();
;       if (i > 0) { ATT_PVK_RD(vB, 1, vp); }
; #pragma unroll
;       for (int d0 = 2; d0 < 4; ++d0) { C0 = __builtin_amdgcn_mfma_f32_32x32x16_bf16(kf[2 * d0], qr[d0], C0, 0, 0, 0); C1 = __builtin_amdgcn_mfma_f32_32x32x16_bf16(kf[2 * d0 + 1], qr[d0], C1, 0, 0, 0); }
;       ATT_SB();
;       if (i > 0) { ATT_PVK(vA, 2); ATT_PVK(vB, 3); } }
;     asm volatile("" : "+v"(C0), "+v"(C1));
; #pragma unroll
;     for (int d = 0; d < ND; ++d) asm volatile("" : "+v"(o[d]));
;     if (grp == 0) ATT_BAR_L(); else ATT_BAR_V(i + 2 < NT);
.Lm1g1_negm_keep:
	s_waitcnt lgkmcnt(15)
	v_mfma_f32_32x32x16_bf16 v[112:127], v[100:103], v[128:131], v[80:95]
	v_mfma_f32_32x32x16_bf16 v[96:111], v[206:209], v[128:131], v[80:95]
	s_waitcnt lgkmcnt(14)
	v_mfma_f32_32x32x16_bf16 v[112:127], v[210:213], v[132:135], v[112:127]
	v_add_u32_e32 v210, s18, v196
	ds_read_b128 v[206:209], v210
	ds_read_b128 v[210:213], v210 offset:4096
	ds_read_b128 v[234:237], v238
	ds_read_b128 v[238:241], v238 offset:4096
	v_mfma_f32_32x32x16_bf16 v[96:111], v[214:217], v[132:135], v[96:111]
	s_waitcnt lgkmcnt(14)
	v_mfma_f32_32x32x16_bf16 v[48:63], v[168:171], v[218:221], v[48:63]
	ds_read_b64_tr_b16 v[214:215], v205 offset:22528
	ds_read_b64_tr_b16 v[216:217], v205 offset:23552
	s_waitcnt lgkmcnt(12)
	v_mfma_f32_32x32x16_bf16 v[64:79], v[168:171], v[222:225], v[64:79]
	ds_read_b64_tr_b16 v[218:219], v242 offset:22528
	ds_read_b64_tr_b16 v[220:221], v242 offset:23552
	s_waitcnt lgkmcnt(10)
	v_mfma_f32_32x32x16_bf16 v[32:47], v[168:171], v[226:229], v[32:47]
	ds_read_b64_tr_b16 v[222:223], v205 offset:30720
	ds_read_b64_tr_b16 v[224:225], v205 offset:31744
	s_waitcnt lgkmcnt(10)
	v_mfma_f32_32x32x16_bf16 v[16:31], v[168:171], v[230:233], v[16:31]
	ds_read_b64_tr_b16 v[168:169], v242 offset:30720
	ds_read_b64_tr_b16 v[170:171], v242 offset:31744
	s_waitcnt lgkmcnt(11)
	v_mfma_f32_32x32x16_bf16 v[112:127], v[206:209], v[136:139], v[112:127]
	s_waitcnt lgkmcnt(10)
	v_mfma_f32_32x32x16_bf16 v[96:111], v[210:213], v[136:139], v[96:111]
	s_waitcnt lgkmcnt(9)
	v_mfma_f32_32x32x16_bf16 v[112:127], v[234:237], v[140:143], v[112:127]
	s_waitcnt lgkmcnt(8)
	v_mfma_f32_32x32x16_bf16 v[96:111], v[238:241], v[140:143], v[96:111]
	v_mfma_f32_32x32x16_bf16 v[48:63], v[164:167], v[156:159], v[48:63]
	ds_read_b64_tr_b16 v[156:157], v248 offset:16384
	ds_read_b64_tr_b16 v[158:159], v248 offset:17408
	v_mfma_f32_32x32x16_bf16 v[64:79], v[164:167], v[152:155], v[64:79]
	ds_read_b64_tr_b16 v[152:153], v249 offset:16384
	ds_read_b64_tr_b16 v[154:155], v249 offset:17408
	v_mfma_f32_32x32x16_bf16 v[32:47], v[164:167], v[148:151], v[32:47]
	ds_read_b64_tr_b16 v[148:149], v248 offset:24576
	ds_read_b64_tr_b16 v[150:151], v248 offset:25600
	v_mfma_f32_32x32x16_bf16 v[16:31], v[164:167], v[144:147], v[16:31]
	ds_read_b64_tr_b16 v[144:145], v249 offset:24576
	ds_read_b64_tr_b16 v[146:147], v249 offset:25600
	s_waitcnt lgkmcnt(14)
	v_mfma_f32_32x32x16_bf16 v[48:63], v[160:163], v[214:217], v[48:63]
	s_waitcnt lgkmcnt(12)
	v_mfma_f32_32x32x16_bf16 v[64:79], v[160:163], v[218:221], v[64:79]
	s_waitcnt lgkmcnt(10)
	v_mfma_f32_32x32x16_bf16 v[32:47], v[160:163], v[222:225], v[32:47]
	s_waitcnt lgkmcnt(8)
	v_mfma_f32_32x32x16_bf16 v[16:31], v[160:163], v[168:171], v[16:31]
	s_cmp_ge_u32 s96, s82
	s_cbranch_scc1 .Lm1_A_drain_g1
	s_waitcnt vmcnt(4) lgkmcnt(0)
	s_barrier
